# N9h + producing wave's first P.V block no longer waits for the next block's transpose reads
# baseline (speedup 1.0000x reference)
; #define SBAR() __builtin_amdgcn_sched_barrier(0)
; #define TRD(Lb, Hb, D0) Lb[0] = tr_read<v_rd_off(D0, 0, 0)>(vb); Hb[0] = tr_read<v_rd_off(D0, 0, 1)>(vb); Lb[1] = tr_read<v_rd_off(D0, 1, 0)>(vb); Hb[1] = tr_read<v_rd_off(D0, 1, 1)>(vb); \
;     Lb[2] = tr_read<v_rd_off(D0, 2, 0)>(vb); Hb[2] = tr_read<v_rd_off(D0, 2, 1)>(vb); Lb[3] = tr_read<v_rd_off(D0, 3, 0)>(vb); Hb[3] = tr_read<v_rd_off(D0, 3, 1)>(vb);
; #define MM(D0, Lb, Hb) o[D0] = __builtin_amdgcn_mfma_f32_32x32x16_bf16(pa0, PK(Lb[0], Hb[0]), o[D0], 0, 0, 0); o[D0] = __builtin_amdgcn_mfma_f32_32x32x16_bf16(pa1, PK(Lb[1], Hb[1]), o[D0], 0, 0, 0); \
;     o[D0] = __builtin_amdgcn_mfma_f32_32x32x16_bf16(pa2, PK(Lb[2], Hb[2]), o[D0], 0, 0, 0); o[D0] = __builtin_amdgcn_mfma_f32_32x32x16_bf16(pa3, PK(Lb[3], Hb[3]), o[D0], 0, 0, 0);
; __device__ __forceinline__ void pv_batched(f32x16* o, int vb, bf16x8 pa0, bf16x8 pa1, bf16x8 pa2, bf16x8 pa3) {
;   s16x4 L0[4], H0[4], L1[4], H1[4];
;     ...
;   TRD(L0, H0, 0) SBAR(); TRD(L1, H1, 1) SBAR();
;   asm volatile("s_waitcnt lgkmcnt(8)" ::: "memory"); SBAR();
;   MM(0, L0, H0) SBAR();
;   TRD(L0, H0, 2) SBAR();
;   asm volatile("s_waitcnt lgkmcnt(8)" ::: "memory"); SBAR();
;   MM(1, L1, H1) SBAR();
;   TRD(L1, H1, 3) SBAR();
;   asm volatile("s_waitcnt lgkmcnt(8)" ::: "memory"); SBAR();
;   MM(2, L0, H0) SBAR();
;   asm volatile("s_waitcnt lgkmcnt(0)" ::: "memory"); SBAR();
;   MM(3, L1, H1) SBAR();
;     ...
; }
.LBB0_1033:
	v_lshl_add_u32 v219, s21, 15, v211
	ds_read_b64_tr_b16 v[242:243], v219 offset:0x200
	ds_read_b64_tr_b16 v[244:245], v219 offset:0xa00
	ds_read_b64_tr_b16 v[246:247], v219 offset:0x1200
	ds_read_b64_tr_b16 v[248:249], v219 offset:0x1a00
	ds_read_b64_tr_b16 v[176:177], v219 offset:0x2200
	ds_read_b64_tr_b16 v[178:179], v219 offset:0x2a00
	ds_read_b64_tr_b16 v[228:229], v219 offset:0x3200
	ds_read_b64_tr_b16 v[230:231], v219 offset:0x3a00
	s_waitcnt lgkmcnt(8)
	s_nop 0
	v_mfma_f32_32x32x16_bf16 v[4:19], v[168:171], v[132:135], v[4:19]
	v_mfma_f32_32x32x16_bf16 v[4:19], v[164:167], v[136:139], v[4:19]
	v_mfma_f32_32x32x16_bf16 v[4:19], v[160:163], v[140:143], v[4:19]
	v_mfma_f32_32x32x16_bf16 v[4:19], v[156:159], v[144:147], v[4:19]
	ds_read_b64_tr_b16 v[220:221], v219 offset:0x400
	ds_read_b64_tr_b16 v[222:223], v219 offset:0xc00
	ds_read_b64_tr_b16 v[224:225], v219 offset:0x1400
	ds_read_b64_tr_b16 v[226:227], v219 offset:0x1c00
	ds_read_b64_tr_b16 v[232:233], v219 offset:0x2400
	ds_read_b64_tr_b16 v[234:235], v219 offset:0x2c00
	ds_read_b64_tr_b16 v[236:237], v219 offset:0x3400
	ds_read_b64_tr_b16 v[238:239], v219 offset:0x3c00
	s_waitcnt lgkmcnt(8)
	v_mfma_f32_32x32x16_bf16 v[52:67], v[168:171], v[242:245], v[52:67]
	v_mfma_f32_32x32x16_bf16 v[52:67], v[164:167], v[246:249], v[52:67]
	v_mfma_f32_32x32x16_bf16 v[52:67], v[160:163], v[176:179], v[52:67]
	v_mfma_f32_32x32x16_bf16 v[52:67], v[156:159], v[228:231], v[52:67]
	ds_read_b64_tr_b16 v[176:177], v219 offset:0x600
	ds_read_b64_tr_b16 v[178:179], v219 offset:0xe00
	ds_read_b64_tr_b16 v[228:229], v219 offset:0x1600
	ds_read_b64_tr_b16 v[230:231], v219 offset:0x1e00
	ds_read_b64_tr_b16 v[240:241], v219 offset:0x2600
	ds_read_b64_tr_b16 v[242:243], v219 offset:0x2e00
	ds_read_b64_tr_b16 v[244:245], v219 offset:0x3600
	ds_read_b64_tr_b16 v[246:247], v219 offset:0x3e00
	s_waitcnt lgkmcnt(8)
	v_mfma_f32_32x32x16_bf16 v[36:51], v[168:171], v[220:223], v[36:51]
	v_mfma_f32_32x32x16_bf16 v[36:51], v[164:167], v[224:227], v[36:51]
	v_mfma_f32_32x32x16_bf16 v[36:51], v[160:163], v[232:235], v[36:51]
	v_mfma_f32_32x32x16_bf16 v[36:51], v[156:159], v[236:239], v[36:51]
	s_waitcnt lgkmcnt(0)
	v_mfma_f32_32x32x16_bf16 v[20:35], v[168:171], v[176:179], v[20:35]
	v_mfma_f32_32x32x16_bf16 v[20:35], v[164:167], v[228:231], v[20:35]
	v_mfma_f32_32x32x16_bf16 v[20:35], v[160:163], v[240:243], v[20:35]
	v_mfma_f32_32x32x16_bf16 v[20:35], v[156:159], v[244:247], v[20:35]
